# convert_tile load loops rewritten: 32 row loads + 16 gain loads in flight per thread instead of hipcc's one-load-per-wait serialization
# speedup vs baseline: 1.0210x; 1.0210x over previous
; #define OPAQUE_TID(v) int v = threadIdx.x; asm volatile("" : "+v"(v))
; DI void convert_tile(const float* __restrict__ src, int K, int N, int kt, int nt, bf16_t* __restrict__ dst, int mode, const float* __restrict__ g, float* lds) {
;   OPAQUE_TID(tid);
; #pragma unroll 8
;   for (int i = 0; i < 32; ++i) { const int e = tid + 512 * i, kk = e >> 8, nn = e & 255; lds[kk * 257 + nn] = src[(size_t)(kt * 64 + kk) * N + nt * 256 + nn] * (g ? g[kt * 64 + kk] : 1.f); }
;   __syncthreads();
; DI void convert_phase(const Params& p, int layer, float* lds) {
;     ...
;     const int ntn = N / 256; const int kt = r / ntn, nt = r % ntn;
;     convert_tile(src, K, N, kt, nt, dst, mode, g, lds);
.LBB0_27:
	s_lshr_b32 s23, s34, 8
	v_cvt_f32_u32_e32 v1, s23
	s_sub_i32 s26, 0, s23
	s_abs_i32 s25, s22
	s_ashr_i32 s24, s22, 31
	v_rcp_iflag_f32_e32 v1, v1
	s_mov_b32 s17, 0
	v_mul_f32_e32 v1, 0x4f7ffffe, v1
	v_cvt_u32_f32_e32 v2, v1
	v_mov_b32_e32 v1, v222
	v_readfirstlane_b32 s27, v2
	s_mul_i32 s26, s26, s27
	s_mul_hi_u32 s26, s27, s26
	s_add_i32 s27, s27, s26
	s_mul_hi_u32 s26, s25, s27
	s_mul_i32 s27, s26, s23
	s_sub_i32 s25, s25, s27
	s_add_i32 s35, s26, 1
	s_sub_i32 s27, s25, s23
	s_cmp_ge_u32 s25, s23
	s_cselect_b32 s26, s35, s26
	s_cselect_b32 s25, s27, s25
	s_add_i32 s27, s26, 1
	s_cmp_ge_u32 s25, s23
	s_cselect_b32 s25, s27, s26
	s_xor_b32 s25, s25, s24
	s_sub_i32 s24, s25, s24
	s_mul_i32 s23, s24, s23
	s_sub_i32 s22, s22, s23
	s_lshl_b32 s22, s22, 8
	s_ashr_i32 s23, s22, 31
	s_lshl_b32 s24, s24, 6
	s_lshl_b64 s[26:27], s[22:23], 2
	s_add_u32 s4, s4, s26
	s_addc_u32 s5, s5, s27
	v_lshlrev_b32_e32 v2, 2, v1
	s_cmp_lg_u64 s[20:21], 0
	v_and_b32_e32 v2, 0x3fc, v2
	s_cselect_b64 s[26:27], -1, 0
	v_lshl_add_u64 v[4:5], s[4:5], 0, v[2:3]
	v_cndmask_b32_e64 v8, 0, 1, s[26:27]
	v_lshrrev_b32_e32 v12, 8, v1
	v_mul_lo_u32 v13, v12, s34
	v_lshl_add_u32 v13, v13, 2, v2
	s_mul_i32 s17, s24, s34
	s_lshl_b32 s17, s17, 2
	s_add_u32 s4, s4, s17
	s_addc_u32 s5, s5, 0
	s_lshl_b32 s17, s34, 3
	global_load_dword v16, v13, s[4:5]
	s_add_u32 s4, s4, s17
	s_addc_u32 s5, s5, 0
	global_load_dword v17, v13, s[4:5]
	s_add_u32 s4, s4, s17
	s_addc_u32 s5, s5, 0
	global_load_dword v18, v13, s[4:5]
	s_add_u32 s4, s4, s17
	s_addc_u32 s5, s5, 0
	global_load_dword v19, v13, s[4:5]
	s_add_u32 s4, s4, s17
	s_addc_u32 s5, s5, 0
	global_load_dword v20, v13, s[4:5]
	s_add_u32 s4, s4, s17
	s_addc_u32 s5, s5, 0
	global_load_dword v21, v13, s[4:5]
	s_add_u32 s4, s4, s17
	s_addc_u32 s5, s5, 0
	global_load_dword v22, v13, s[4:5]
	s_add_u32 s4, s4, s17
	s_addc_u32 s5, s5, 0
	global_load_dword v23, v13, s[4:5]
	s_add_u32 s4, s4, s17
	s_addc_u32 s5, s5, 0
	global_load_dword v24, v13, s[4:5]
	s_add_u32 s4, s4, s17
	s_addc_u32 s5, s5, 0
	global_load_dword v25, v13, s[4:5]
	s_add_u32 s4, s4, s17
	s_addc_u32 s5, s5, 0
	global_load_dword v26, v13, s[4:5]
	s_add_u32 s4, s4, s17
	s_addc_u32 s5, s5, 0
	global_load_dword v27, v13, s[4:5]
	s_add_u32 s4, s4, s17
	s_addc_u32 s5, s5, 0
	global_load_dword v28, v13, s[4:5]
	s_add_u32 s4, s4, s17
	s_addc_u32 s5, s5, 0
	global_load_dword v29, v13, s[4:5]
	s_add_u32 s4, s4, s17
	s_addc_u32 s5, s5, 0
	global_load_dword v30, v13, s[4:5]
	s_add_u32 s4, s4, s17
	s_addc_u32 s5, s5, 0
	global_load_dword v31, v13, s[4:5]
	s_add_u32 s4, s4, s17
	s_addc_u32 s5, s5, 0
	global_load_dword v32, v13, s[4:5]
	s_add_u32 s4, s4, s17
	s_addc_u32 s5, s5, 0
	global_load_dword v33, v13, s[4:5]
	s_add_u32 s4, s4, s17
	s_addc_u32 s5, s5, 0
	global_load_dword v34, v13, s[4:5]
	s_add_u32 s4, s4, s17
	s_addc_u32 s5, s5, 0
	global_load_dword v35, v13, s[4:5]
	s_add_u32 s4, s4, s17
	s_addc_u32 s5, s5, 0
	global_load_dword v36, v13, s[4:5]
	s_add_u32 s4, s4, s17
	s_addc_u32 s5, s5, 0
	global_load_dword v37, v13, s[4:5]
	s_add_u32 s4, s4, s17
	s_addc_u32 s5, s5, 0
	global_load_dword v38, v13, s[4:5]
	s_add_u32 s4, s4, s17
	s_addc_u32 s5, s5, 0
	global_load_dword v39, v13, s[4:5]
	s_add_u32 s4, s4, s17
	s_addc_u32 s5, s5, 0
	global_load_dword v40, v13, s[4:5]
	s_add_u32 s4, s4, s17
	s_addc_u32 s5, s5, 0
	global_load_dword v41, v13, s[4:5]
	s_add_u32 s4, s4, s17
	s_addc_u32 s5, s5, 0
	global_load_dword v42, v13, s[4:5]
	s_add_u32 s4, s4, s17
	s_addc_u32 s5, s5, 0
	global_load_dword v43, v13, s[4:5]
	s_add_u32 s4, s4, s17
	s_addc_u32 s5, s5, 0
	global_load_dword v44, v13, s[4:5]
	s_add_u32 s4, s4, s17
	s_addc_u32 s5, s5, 0
	global_load_dword v45, v13, s[4:5]
	s_add_u32 s4, s4, s17
	s_addc_u32 s5, s5, 0
	global_load_dword v46, v13, s[4:5]
	s_add_u32 s4, s4, s17
	s_addc_u32 s5, s5, 0
	global_load_dword v47, v13, s[4:5]
	v_mul_u32_u24_e32 v12, 0x404, v12
	v_add_u32_e32 v12, v12, v2
	s_and_b64 vcc, exec, s[26:27]
	s_cbranch_vccz .Lcv0_nog
; DI void convert_tile(const float* __restrict__ src, int K, int N, int kt, int nt, bf16_t* __restrict__ dst, int mode, const float* __restrict__ g, float* lds) {
;     ...
;   for (int i = 0; i < 32; ++i) { const int e = tid + 512 * i, kk = e >> 8, nn = e & 255; lds[kk * 257 + nn] = src[(size_t)(kt * 64 + kk) * N + nt * 256 + nn] * (g ? g[kt * 64 + kk] : 1.f); }
	s_lshl_b32 s17, s24, 2
	s_add_u32 s36, s20, s17
	s_addc_u32 s37, s21, 0
	global_load_dwordx4 v[48:51], v3, s[36:37]
	global_load_dwordx4 v[52:55], v3, s[36:37] offset:16
	global_load_dwordx4 v[56:59], v3, s[36:37] offset:32
	global_load_dwordx4 v[60:63], v3, s[36:37] offset:48
	global_load_dwordx4 v[64:67], v3, s[36:37] offset:64
	global_load_dwordx4 v[68:71], v3, s[36:37] offset:80
	global_load_dwordx4 v[72:75], v3, s[36:37] offset:96
	global_load_dwordx4 v[76:79], v3, s[36:37] offset:112
	global_load_dwordx4 v[80:83], v3, s[36:37] offset:128
	global_load_dwordx4 v[84:87], v3, s[36:37] offset:144
	global_load_dwordx4 v[88:91], v3, s[36:37] offset:160
	global_load_dwordx4 v[92:95], v3, s[36:37] offset:176
	global_load_dwordx4 v[96:99], v3, s[36:37] offset:192
	global_load_dwordx4 v[100:103], v3, s[36:37] offset:208
	global_load_dwordx4 v[104:107], v3, s[36:37] offset:224
	global_load_dwordx4 v[108:111], v3, s[36:37] offset:240
	v_cmp_gt_u32_e32 vcc, 0x100, v1
	s_nop 1
	s_waitcnt vmcnt(0)
	v_cndmask_b32_e32 v14, v49, v48, vcc
	v_mul_f32_e32 v16, v16, v14
	ds_write_b32 v12, v16
	v_cndmask_b32_e32 v14, v51, v50, vcc
	v_mul_f32_e32 v17, v17, v14
	ds_write_b32 v12, v17 offset:2056
	v_cndmask_b32_e32 v14, v53, v52, vcc
	v_mul_f32_e32 v18, v18, v14
	ds_write_b32 v12, v18 offset:4112
	v_cndmask_b32_e32 v14, v55, v54, vcc
	v_mul_f32_e32 v19, v19, v14
	ds_write_b32 v12, v19 offset:6168
	v_cndmask_b32_e32 v14, v57, v56, vcc
	v_mul_f32_e32 v20, v20, v14
	ds_write_b32 v12, v20 offset:8224
	v_cndmask_b32_e32 v14, v59, v58, vcc
	v_mul_f32_e32 v21, v21, v14
	ds_write_b32 v12, v21 offset:10280
	v_cndmask_b32_e32 v14, v61, v60, vcc
	v_mul_f32_e32 v22, v22, v14
	ds_write_b32 v12, v22 offset:12336
	v_cndmask_b32_e32 v14, v63, v62, vcc
	v_mul_f32_e32 v23, v23, v14
	ds_write_b32 v12, v23 offset:14392
	v_cndmask_b32_e32 v14, v65, v64, vcc
	v_mul_f32_e32 v24, v24, v14
	ds_write_b32 v12, v24 offset:16448
	v_cndmask_b32_e32 v14, v67, v66, vcc
	v_mul_f32_e32 v25, v25, v14
	ds_write_b32 v12, v25 offset:18504
	v_cndmask_b32_e32 v14, v69, v68, vcc
	v_mul_f32_e32 v26, v26, v14
	ds_write_b32 v12, v26 offset:20560
	v_cndmask_b32_e32 v14, v71, v70, vcc
	v_mul_f32_e32 v27, v27, v14
	ds_write_b32 v12, v27 offset:22616
	v_cndmask_b32_e32 v14, v73, v72, vcc
	v_mul_f32_e32 v28, v28, v14
	ds_write_b32 v12, v28 offset:24672
	v_cndmask_b32_e32 v14, v75, v74, vcc
	v_mul_f32_e32 v29, v29, v14
	ds_write_b32 v12, v29 offset:26728
	v_cndmask_b32_e32 v14, v77, v76, vcc
	v_mul_f32_e32 v30, v30, v14
	ds_write_b32 v12, v30 offset:28784
	v_cndmask_b32_e32 v14, v79, v78, vcc
	v_mul_f32_e32 v31, v31, v14
	ds_write_b32 v12, v31 offset:30840
	v_cndmask_b32_e32 v14, v81, v80, vcc
	v_mul_f32_e32 v32, v32, v14
	ds_write_b32 v12, v32 offset:32896
	v_cndmask_b32_e32 v14, v83, v82, vcc
	v_mul_f32_e32 v33, v33, v14
	ds_write_b32 v12, v33 offset:34952
	v_cndmask_b32_e32 v14, v85, v84, vcc
	v_mul_f32_e32 v34, v34, v14
	ds_write_b32 v12, v34 offset:37008
	v_cndmask_b32_e32 v14, v87, v86, vcc
	v_mul_f32_e32 v35, v35, v14
	ds_write_b32 v12, v35 offset:39064
	v_cndmask_b32_e32 v14, v89, v88, vcc
	v_mul_f32_e32 v36, v36, v14
	ds_write_b32 v12, v36 offset:41120
	v_cndmask_b32_e32 v14, v91, v90, vcc
	v_mul_f32_e32 v37, v37, v14
	ds_write_b32 v12, v37 offset:43176
	v_cndmask_b32_e32 v14, v93, v92, vcc
	v_mul_f32_e32 v38, v38, v14
	ds_write_b32 v12, v38 offset:45232
	v_cndmask_b32_e32 v14, v95, v94, vcc
	v_mul_f32_e32 v39, v39, v14
	ds_write_b32 v12, v39 offset:47288
	v_cndmask_b32_e32 v14, v97, v96, vcc
	v_mul_f32_e32 v40, v40, v14
	ds_write_b32 v12, v40 offset:49344
	v_cndmask_b32_e32 v14, v99, v98, vcc
	v_mul_f32_e32 v41, v41, v14
	ds_write_b32 v12, v41 offset:51400
	v_cndmask_b32_e32 v14, v101, v100, vcc
	v_mul_f32_e32 v42, v42, v14
	ds_write_b32 v12, v42 offset:53456
	v_cndmask_b32_e32 v14, v103, v102, vcc
	v_mul_f32_e32 v43, v43, v14
	ds_write_b32 v12, v43 offset:55512
	v_cndmask_b32_e32 v14, v105, v104, vcc
	v_mul_f32_e32 v44, v44, v14
	ds_write_b32 v12, v44 offset:57568
	v_cndmask_b32_e32 v14, v107, v106, vcc
	v_mul_f32_e32 v45, v45, v14
	ds_write_b32 v12, v45 offset:59624
	v_cndmask_b32_e32 v14, v109, v108, vcc
	v_mul_f32_e32 v46, v46, v14
	ds_write_b32 v12, v46 offset:61680
	v_cndmask_b32_e32 v14, v111, v110, vcc
	v_mul_f32_e32 v47, v47, v14
	ds_write_b32 v12, v47 offset:63736
	s_branch .LBB0_7
.Lcv0_nog:
	s_waitcnt vmcnt(0)
	ds_write_b32 v12, v16
	ds_write_b32 v12, v17 offset:2056
	ds_write_b32 v12, v18 offset:4112
	ds_write_b32 v12, v19 offset:6168
	ds_write_b32 v12, v20 offset:8224
	ds_write_b32 v12, v21 offset:10280
	ds_write_b32 v12, v22 offset:12336
	ds_write_b32 v12, v23 offset:14392
	ds_write_b32 v12, v24 offset:16448
	ds_write_b32 v12, v25 offset:18504
	ds_write_b32 v12, v26 offset:20560
	ds_write_b32 v12, v27 offset:22616
	ds_write_b32 v12, v28 offset:24672
	ds_write_b32 v12, v29 offset:26728
	ds_write_b32 v12, v30 offset:28784
	ds_write_b32 v12, v31 offset:30840
	ds_write_b32 v12, v32 offset:32896
	ds_write_b32 v12, v33 offset:34952
	ds_write_b32 v12, v34 offset:37008
	ds_write_b32 v12, v35 offset:39064
	ds_write_b32 v12, v36 offset:41120
	ds_write_b32 v12, v37 offset:43176
	ds_write_b32 v12, v38 offset:45232
	ds_write_b32 v12, v39 offset:47288
	ds_write_b32 v12, v40 offset:49344
	ds_write_b32 v12, v41 offset:51400
	ds_write_b32 v12, v42 offset:53456
	ds_write_b32 v12, v43 offset:55512
	ds_write_b32 v12, v44 offset:57568
	ds_write_b32 v12, v45 offset:59624
	ds_write_b32 v12, v46 offset:61680
	ds_write_b32 v12, v47 offset:63736
	s_branch .LBB0_7

; DI void convert_tile(const float* __restrict__ src, int K, int N, int kt, int nt, bf16_t* __restrict__ dst, int mode, const float* __restrict__ g, float* lds) {
;     ...
;   for (int i = 0; i < 32; ++i) { const int e = tid + 512 * i, kk = e >> 8, nn = e & 255; lds[kk * 257 + nn] = src[(size_t)(kt * 64 + kk) * N + nt * 256 + nn] * (g ? g[kt * 64 + kk] : 1.f); }
; DI void convert_phase(const Params& p, int layer, float* lds) {
;     ...
;     const int ntn = N / 256; const int kt = r / ntn, nt = r % ntn;
;     convert_tile(src, K, N, kt, nt, dst, mode, g, lds);
.LBB0_782:
	s_lshr_b32 s9, s6, 8
	v_cvt_f32_u32_e32 v0, s9
	s_sub_i32 s14, 0, s9
	s_abs_i32 s13, s8
	s_ashr_i32 s12, s8, 31
	v_rcp_iflag_f32_e32 v0, v0
	v_mov_b32_e32 v6, v222
	s_mov_b32 s7, 0
	v_mul_f32_e32 v0, 0x4f7ffffe, v0
	v_cvt_u32_f32_e32 v0, v0
	s_nop 0
	v_readfirstlane_b32 s15, v0
	s_mul_i32 s14, s14, s15
	s_mul_hi_u32 s14, s15, s14
	s_add_i32 s15, s15, s14
	s_mul_hi_u32 s14, s13, s15
	s_mul_i32 s15, s14, s9
	s_sub_i32 s13, s13, s15
	s_add_i32 s16, s14, 1
	s_sub_i32 s15, s13, s9
	s_cmp_ge_u32 s13, s9
	s_cselect_b32 s14, s16, s14
	s_cselect_b32 s13, s15, s13
	s_add_i32 s15, s14, 1
	s_cmp_ge_u32 s13, s9
	s_cselect_b32 s13, s15, s14
	s_xor_b32 s13, s13, s12
	s_sub_i32 s12, s13, s12
	s_mul_i32 s9, s12, s9
	s_sub_i32 s8, s8, s9
	s_lshl_b32 s38, s8, 8
	s_ashr_i32 s39, s38, 31
	s_lshl_b32 s40, s12, 6
	s_lshl_b64 s[8:9], s[38:39], 2
	s_add_u32 s0, s0, s8
	s_addc_u32 s1, s1, s9
	v_lshlrev_b32_e32 v0, 2, v6
	v_and_b32_e32 v0, 0x3fc, v0
	s_cmp_lg_u64 s[36:37], 0
	v_lshl_add_u64 v[2:3], s[0:1], 0, v[0:1]
	s_cselect_b64 s[78:79], -1, 0
	v_lshrrev_b32_e32 v12, 8, v6
	v_mul_lo_u32 v13, v12, s6
	v_lshl_add_u32 v13, v13, 2, v0
	s_mul_i32 s7, s40, s6
	s_lshl_b32 s7, s7, 2
	s_add_u32 s0, s0, s7
	s_addc_u32 s1, s1, 0
	s_lshl_b32 s7, s6, 3
	global_load_dword v16, v13, s[0:1]
	s_add_u32 s0, s0, s7
	s_addc_u32 s1, s1, 0
	global_load_dword v17, v13, s[0:1]
	s_add_u32 s0, s0, s7
	s_addc_u32 s1, s1, 0
	global_load_dword v18, v13, s[0:1]
	s_add_u32 s0, s0, s7
	s_addc_u32 s1, s1, 0
	global_load_dword v19, v13, s[0:1]
	s_add_u32 s0, s0, s7
	s_addc_u32 s1, s1, 0
	global_load_dword v20, v13, s[0:1]
	s_add_u32 s0, s0, s7
	s_addc_u32 s1, s1, 0
	global_load_dword v21, v13, s[0:1]
	s_add_u32 s0, s0, s7
	s_addc_u32 s1, s1, 0
	global_load_dword v22, v13, s[0:1]
	s_add_u32 s0, s0, s7
	s_addc_u32 s1, s1, 0
	global_load_dword v23, v13, s[0:1]
	s_add_u32 s0, s0, s7
	s_addc_u32 s1, s1, 0
	global_load_dword v24, v13, s[0:1]
	s_add_u32 s0, s0, s7
	s_addc_u32 s1, s1, 0
	global_load_dword v25, v13, s[0:1]
	s_add_u32 s0, s0, s7
	s_addc_u32 s1, s1, 0
	global_load_dword v26, v13, s[0:1]
	s_add_u32 s0, s0, s7
	s_addc_u32 s1, s1, 0
	global_load_dword v27, v13, s[0:1]
	s_add_u32 s0, s0, s7
	s_addc_u32 s1, s1, 0
	global_load_dword v28, v13, s[0:1]
	s_add_u32 s0, s0, s7
	s_addc_u32 s1, s1, 0
	global_load_dword v29, v13, s[0:1]
	s_add_u32 s0, s0, s7
	s_addc_u32 s1, s1, 0
	global_load_dword v30, v13, s[0:1]
	s_add_u32 s0, s0, s7
	s_addc_u32 s1, s1, 0
	global_load_dword v31, v13, s[0:1]
	s_add_u32 s0, s0, s7
	s_addc_u32 s1, s1, 0
	global_load_dword v32, v13, s[0:1]
	s_add_u32 s0, s0, s7
	s_addc_u32 s1, s1, 0
	global_load_dword v33, v13, s[0:1]
	s_add_u32 s0, s0, s7
	s_addc_u32 s1, s1, 0
	global_load_dword v34, v13, s[0:1]
	s_add_u32 s0, s0, s7
	s_addc_u32 s1, s1, 0
	global_load_dword v35, v13, s[0:1]
	s_add_u32 s0, s0, s7
	s_addc_u32 s1, s1, 0
	global_load_dword v36, v13, s[0:1]
	s_add_u32 s0, s0, s7
	s_addc_u32 s1, s1, 0
	global_load_dword v37, v13, s[0:1]
	s_add_u32 s0, s0, s7
	s_addc_u32 s1, s1, 0
	global_load_dword v38, v13, s[0:1]
	s_add_u32 s0, s0, s7
	s_addc_u32 s1, s1, 0
	global_load_dword v39, v13, s[0:1]
	s_add_u32 s0, s0, s7
	s_addc_u32 s1, s1, 0
	global_load_dword v40, v13, s[0:1]
	s_add_u32 s0, s0, s7
	s_addc_u32 s1, s1, 0
	global_load_dword v41, v13, s[0:1]
	s_add_u32 s0, s0, s7
	s_addc_u32 s1, s1, 0
	global_load_dword v42, v13, s[0:1]
	s_add_u32 s0, s0, s7
	s_addc_u32 s1, s1, 0
	global_load_dword v43, v13, s[0:1]
	s_add_u32 s0, s0, s7
	s_addc_u32 s1, s1, 0
	global_load_dword v44, v13, s[0:1]
	s_add_u32 s0, s0, s7
	s_addc_u32 s1, s1, 0
	global_load_dword v45, v13, s[0:1]
	s_add_u32 s0, s0, s7
	s_addc_u32 s1, s1, 0
	global_load_dword v46, v13, s[0:1]
	s_add_u32 s0, s0, s7
	s_addc_u32 s1, s1, 0
	global_load_dword v47, v13, s[0:1]
	v_mul_u32_u24_e32 v12, 0x404, v12
	v_add_u32_e32 v12, v12, v0
	s_and_b64 vcc, exec, s[78:79]
	s_cbranch_vccz .Lcv1_nog
; DI void convert_tile(const float* __restrict__ src, int K, int N, int kt, int nt, bf16_t* __restrict__ dst, int mode, const float* __restrict__ g, float* lds) {
;     ...
;   for (int i = 0; i < 32; ++i) { const int e = tid + 512 * i, kk = e >> 8, nn = e & 255; lds[kk * 257 + nn] = src[(size_t)(kt * 64 + kk) * N + nt * 256 + nn] * (g ? g[kt * 64 + kk] : 1.f); }
	s_lshl_b32 s7, s40, 2
	s_add_u32 s8, s36, s7
	s_addc_u32 s9, s37, 0
	global_load_dwordx4 v[48:51], v1, s[8:9]
	global_load_dwordx4 v[52:55], v1, s[8:9] offset:16
	global_load_dwordx4 v[56:59], v1, s[8:9] offset:32
	global_load_dwordx4 v[60:63], v1, s[8:9] offset:48
	global_load_dwordx4 v[64:67], v1, s[8:9] offset:64
	global_load_dwordx4 v[68:71], v1, s[8:9] offset:80
	global_load_dwordx4 v[72:75], v1, s[8:9] offset:96
	global_load_dwordx4 v[76:79], v1, s[8:9] offset:112
	global_load_dwordx4 v[80:83], v1, s[8:9] offset:128
	global_load_dwordx4 v[84:87], v1, s[8:9] offset:144
	global_load_dwordx4 v[88:91], v1, s[8:9] offset:160
	global_load_dwordx4 v[92:95], v1, s[8:9] offset:176
	global_load_dwordx4 v[96:99], v1, s[8:9] offset:192
	global_load_dwordx4 v[100:103], v1, s[8:9] offset:208
	global_load_dwordx4 v[104:107], v1, s[8:9] offset:224
	global_load_dwordx4 v[108:111], v1, s[8:9] offset:240
	v_cmp_gt_u32_e32 vcc, 0x100, v6
	s_nop 1
	s_waitcnt vmcnt(0)
	v_cndmask_b32_e32 v14, v49, v48, vcc
	v_mul_f32_e32 v16, v16, v14
	ds_write_b32 v12, v16
	v_cndmask_b32_e32 v14, v51, v50, vcc
	v_mul_f32_e32 v17, v17, v14
	ds_write_b32 v12, v17 offset:2056
	v_cndmask_b32_e32 v14, v53, v52, vcc
	v_mul_f32_e32 v18, v18, v14
	ds_write_b32 v12, v18 offset:4112
	v_cndmask_b32_e32 v14, v55, v54, vcc
	v_mul_f32_e32 v19, v19, v14
	ds_write_b32 v12, v19 offset:6168
	v_cndmask_b32_e32 v14, v57, v56, vcc
	v_mul_f32_e32 v20, v20, v14
	ds_write_b32 v12, v20 offset:8224
	v_cndmask_b32_e32 v14, v59, v58, vcc
	v_mul_f32_e32 v21, v21, v14
	ds_write_b32 v12, v21 offset:10280
	v_cndmask_b32_e32 v14, v61, v60, vcc
	v_mul_f32_e32 v22, v22, v14
	ds_write_b32 v12, v22 offset:12336
	v_cndmask_b32_e32 v14, v63, v62, vcc
	v_mul_f32_e32 v23, v23, v14
	ds_write_b32 v12, v23 offset:14392
	v_cndmask_b32_e32 v14, v65, v64, vcc
	v_mul_f32_e32 v24, v24, v14
	ds_write_b32 v12, v24 offset:16448
	v_cndmask_b32_e32 v14, v67, v66, vcc
	v_mul_f32_e32 v25, v25, v14
	ds_write_b32 v12, v25 offset:18504
	v_cndmask_b32_e32 v14, v69, v68, vcc
	v_mul_f32_e32 v26, v26, v14
	ds_write_b32 v12, v26 offset:20560
	v_cndmask_b32_e32 v14, v71, v70, vcc
	v_mul_f32_e32 v27, v27, v14
	ds_write_b32 v12, v27 offset:22616
	v_cndmask_b32_e32 v14, v73, v72, vcc
	v_mul_f32_e32 v28, v28, v14
	ds_write_b32 v12, v28 offset:24672
	v_cndmask_b32_e32 v14, v75, v74, vcc
	v_mul_f32_e32 v29, v29, v14
	ds_write_b32 v12, v29 offset:26728
	v_cndmask_b32_e32 v14, v77, v76, vcc
	v_mul_f32_e32 v30, v30, v14
	ds_write_b32 v12, v30 offset:28784
	v_cndmask_b32_e32 v14, v79, v78, vcc
	v_mul_f32_e32 v31, v31, v14
	ds_write_b32 v12, v31 offset:30840
	v_cndmask_b32_e32 v14, v81, v80, vcc
	v_mul_f32_e32 v32, v32, v14
	ds_write_b32 v12, v32 offset:32896
	v_cndmask_b32_e32 v14, v83, v82, vcc
	v_mul_f32_e32 v33, v33, v14
	ds_write_b32 v12, v33 offset:34952
	v_cndmask_b32_e32 v14, v85, v84, vcc
	v_mul_f32_e32 v34, v34, v14
	ds_write_b32 v12, v34 offset:37008
	v_cndmask_b32_e32 v14, v87, v86, vcc
	v_mul_f32_e32 v35, v35, v14
	ds_write_b32 v12, v35 offset:39064
	v_cndmask_b32_e32 v14, v89, v88, vcc
	v_mul_f32_e32 v36, v36, v14
	ds_write_b32 v12, v36 offset:41120
	v_cndmask_b32_e32 v14, v91, v90, vcc
	v_mul_f32_e32 v37, v37, v14
	ds_write_b32 v12, v37 offset:43176
	v_cndmask_b32_e32 v14, v93, v92, vcc
	v_mul_f32_e32 v38, v38, v14
	ds_write_b32 v12, v38 offset:45232
	v_cndmask_b32_e32 v14, v95, v94, vcc
	v_mul_f32_e32 v39, v39, v14
	ds_write_b32 v12, v39 offset:47288
	v_cndmask_b32_e32 v14, v97, v96, vcc
	v_mul_f32_e32 v40, v40, v14
	ds_write_b32 v12, v40 offset:49344
	v_cndmask_b32_e32 v14, v99, v98, vcc
	v_mul_f32_e32 v41, v41, v14
	ds_write_b32 v12, v41 offset:51400
	v_cndmask_b32_e32 v14, v101, v100, vcc
	v_mul_f32_e32 v42, v42, v14
	ds_write_b32 v12, v42 offset:53456
	v_cndmask_b32_e32 v14, v103, v102, vcc
	v_mul_f32_e32 v43, v43, v14
	ds_write_b32 v12, v43 offset:55512
	v_cndmask_b32_e32 v14, v105, v104, vcc
	v_mul_f32_e32 v44, v44, v14
	ds_write_b32 v12, v44 offset:57568
	v_cndmask_b32_e32 v14, v107, v106, vcc
	v_mul_f32_e32 v45, v45, v14
	ds_write_b32 v12, v45 offset:59624
	v_cndmask_b32_e32 v14, v109, v108, vcc
	v_mul_f32_e32 v46, v46, v14
	ds_write_b32 v12, v46 offset:61680
	v_cndmask_b32_e32 v14, v111, v110, vcc
	v_mul_f32_e32 v47, v47, v14
	ds_write_b32 v12, v47 offset:63736
	s_branch .LBB0_762
